# G5 layer-0: latent tiles 2 per block + context tiles as deterministic split-K (8 slices) third unit, partials reduced in next norm_rows
# speedup vs baseline: 1.0464x; 1.0043x over previous
; #define p (kparams())
; __device__ __forceinline__ void norm_rows(const int wv_, KPR p, int l, int src_layer, const float* gvec, int part_shift, int part_scale, bool copy_ctx) {
;     ...
;   for (int row = blockIdx.x * 8 + wid; row < T; row += gridDim.x * 8) {
;     const float* x = xrow_ptr(p, src_layer, row);
;     const float* mw = modl + (size_t)row_who(row) * 12288;
;     f32x4 v[8]; float ss = 0.f;
; #pragma unroll
;     for (int j = 0; j < 8; ++j) { v[j] = *(const f32x4*)(x + lane * 4 + 256 * j); ss += v[j][0] * v[j][0] + v[j][1] * v[j][1] + v[j][2] * v[j][2] + v[j][3] * v[j][3]; }
;     const float rstd = rsqrtf(wave_sum(ss) * (1.f / D) + 1e-6f);
.LBB0_138:
	s_or_b64 exec, exec, s[20:21]
	v_ashrrev_i32_e32 v5, 31, v4
	v_lshlrev_b64 v[4:5], 13, v[4:5]
	v_lshl_add_u64 v[4:5], v[6:7], 0, v[4:5]
	v_lshlrev_b32_e32 v66, 2, v36
	v_mov_b32_e32 v67, v2
	v_lshl_add_u64 v[4:5], v[4:5], 0, v[66:67]
	global_load_dwordx4 v[32:35], v[4:5], off
	global_load_dwordx4 v[28:31], v[4:5], off offset:1024
	global_load_dwordx4 v[24:27], v[4:5], off offset:2048
	global_load_dwordx4 v[20:23], v[4:5], off offset:3072
	v_add_co_u32_e32 v4, vcc, s52, v4
	s_waitcnt vmcnt(3)
	v_mul_f32_e32 v53, v33, v33
	v_addc_co_u32_e32 v5, vcc, 0, v5, vcc
	global_load_dwordx4 v[16:19], v[4:5], off
	global_load_dwordx4 v[12:15], v[4:5], off offset:1024
	global_load_dwordx4 v[8:11], v[4:5], off offset:2048
	s_nop 0
	global_load_dwordx4 v[4:7], v[4:5], off offset:3072
	v_cmp_eq_u32_e64 s[24:25], 4, v3
	s_nop 3
	s_andn2_b64 s[24:25], s[24:25], s[6:7]
	s_and_b64 vcc, exec, s[24:25]
	s_cbranch_vccz .Lnr_skip
	v_readlane_b32 s24, v242, 62
	s_cmp_lg_u32 s24, 0
	s_cbranch_scc0 .Lnr_skip
	s_add_u32 s22, s16, 0x9ce8000
	s_addc_u32 s23, s17, 0
	s_sub_u32 s20, s14, 0x2000
	s_subb_u32 s21, s15, 0
	v_lshl_add_u32 v222, v1, 8, v37
	v_lshl_add_u32 v222, v222, 13, v66
	v_mov_b32_e32 v223, 0
	v_lshl_add_u64 v[222:223], v[222:223], 0, s[22:23]
	s_mov_b64 s[24:25], 0x1000
	v_lshl_add_u64 v[224:225], v[222:223], 0, s[24:25]
	v_mov_b32_e32 v226, v66
	v_mov_b32_e32 v227, 0
	v_lshl_add_u64 v[226:227], v[226:227], 0, s[20:21]
	v_lshl_add_u64 v[228:229], v[226:227], 0, s[24:25]
	s_mov_b32 s24, 0x800000
	global_load_dwordx4 v[88:91], v[222:223], off
	global_load_dwordx4 v[92:95], v[222:223], off offset:1024
	global_load_dwordx4 v[96:99], v[222:223], off offset:2048
	global_load_dwordx4 v[100:103], v[222:223], off offset:3072
	global_load_dwordx4 v[104:107], v[224:225], off
	global_load_dwordx4 v[108:111], v[224:225], off offset:1024
	global_load_dwordx4 v[112:115], v[224:225], off offset:2048
	global_load_dwordx4 v[116:119], v[224:225], off offset:3072
	v_lshl_add_u64 v[222:223], v[222:223], 0, s[24:25]
	v_lshl_add_u64 v[224:225], v[224:225], 0, s[24:25]
	global_load_dwordx4 v[120:123], v[222:223], off
	global_load_dwordx4 v[124:127], v[222:223], off offset:1024
	global_load_dwordx4 v[128:131], v[222:223], off offset:2048
	global_load_dwordx4 v[132:135], v[222:223], off offset:3072
	global_load_dwordx4 v[136:139], v[224:225], off
	global_load_dwordx4 v[140:143], v[224:225], off offset:1024
	global_load_dwordx4 v[144:147], v[224:225], off offset:2048
	global_load_dwordx4 v[148:151], v[224:225], off offset:3072
	v_lshl_add_u64 v[222:223], v[222:223], 0, s[24:25]
	v_lshl_add_u64 v[224:225], v[224:225], 0, s[24:25]
	global_load_dwordx4 v[190:193], v[222:223], off
	global_load_dwordx4 v[194:197], v[222:223], off offset:1024
	global_load_dwordx4 v[198:201], v[222:223], off offset:2048
	global_load_dwordx4 v[202:205], v[222:223], off offset:3072
	global_load_dwordx4 v[206:209], v[224:225], off
	global_load_dwordx4 v[210:213], v[224:225], off offset:1024
	global_load_dwordx4 v[214:217], v[224:225], off offset:2048
	global_load_dwordx4 v[218:221], v[224:225], off offset:3072
	v_lshl_add_u64 v[222:223], v[222:223], 0, s[24:25]
	v_lshl_add_u64 v[224:225], v[224:225], 0, s[24:25]
	s_waitcnt vmcnt(0)
	v_pk_add_f32 v[88:89], v[88:89], v[120:121]
	v_pk_add_f32 v[90:91], v[90:91], v[122:123]
	v_pk_add_f32 v[92:93], v[92:93], v[124:125]
	v_pk_add_f32 v[94:95], v[94:95], v[126:127]
	v_pk_add_f32 v[96:97], v[96:97], v[128:129]
	v_pk_add_f32 v[98:99], v[98:99], v[130:131]
	v_pk_add_f32 v[100:101], v[100:101], v[132:133]
	v_pk_add_f32 v[102:103], v[102:103], v[134:135]
	v_pk_add_f32 v[104:105], v[104:105], v[136:137]
	v_pk_add_f32 v[106:107], v[106:107], v[138:139]
	v_pk_add_f32 v[108:109], v[108:109], v[140:141]
	v_pk_add_f32 v[110:111], v[110:111], v[142:143]
	v_pk_add_f32 v[112:113], v[112:113], v[144:145]
	v_pk_add_f32 v[114:115], v[114:115], v[146:147]
	v_pk_add_f32 v[116:117], v[116:117], v[148:149]
	v_pk_add_f32 v[118:119], v[118:119], v[150:151]
	v_pk_add_f32 v[88:89], v[88:89], v[190:191]
	v_pk_add_f32 v[90:91], v[90:91], v[192:193]
	v_pk_add_f32 v[92:93], v[92:93], v[194:195]
	v_pk_add_f32 v[94:95], v[94:95], v[196:197]
	v_pk_add_f32 v[96:97], v[96:97], v[198:199]
	v_pk_add_f32 v[98:99], v[98:99], v[200:201]
	v_pk_add_f32 v[100:101], v[100:101], v[202:203]
	v_pk_add_f32 v[102:103], v[102:103], v[204:205]
	v_pk_add_f32 v[104:105], v[104:105], v[206:207]
	v_pk_add_f32 v[106:107], v[106:107], v[208:209]
	v_pk_add_f32 v[108:109], v[108:109], v[210:211]
	v_pk_add_f32 v[110:111], v[110:111], v[212:213]
	v_pk_add_f32 v[112:113], v[112:113], v[214:215]
	v_pk_add_f32 v[114:115], v[114:115], v[216:217]
	v_pk_add_f32 v[116:117], v[116:117], v[218:219]
	v_pk_add_f32 v[118:119], v[118:119], v[220:221]
	global_load_dwordx4 v[120:123], v[222:223], off
	global_load_dwordx4 v[124:127], v[222:223], off offset:1024
	global_load_dwordx4 v[128:131], v[222:223], off offset:2048
	global_load_dwordx4 v[132:135], v[222:223], off offset:3072
	global_load_dwordx4 v[136:139], v[224:225], off
	global_load_dwordx4 v[140:143], v[224:225], off offset:1024
	global_load_dwordx4 v[144:147], v[224:225], off offset:2048
	global_load_dwordx4 v[148:151], v[224:225], off offset:3072
	v_lshl_add_u64 v[222:223], v[222:223], 0, s[24:25]
	v_lshl_add_u64 v[224:225], v[224:225], 0, s[24:25]
	global_load_dwordx4 v[190:193], v[222:223], off
	global_load_dwordx4 v[194:197], v[222:223], off offset:1024
	global_load_dwordx4 v[198:201], v[222:223], off offset:2048
	global_load_dwordx4 v[202:205], v[222:223], off offset:3072
	global_load_dwordx4 v[206:209], v[224:225], off
	global_load_dwordx4 v[210:213], v[224:225], off offset:1024
	global_load_dwordx4 v[214:217], v[224:225], off offset:2048
	global_load_dwordx4 v[218:221], v[224:225], off offset:3072
	v_lshl_add_u64 v[222:223], v[222:223], 0, s[24:25]
	v_lshl_add_u64 v[224:225], v[224:225], 0, s[24:25]
	s_waitcnt vmcnt(0)
; __device__ __forceinline__ void norm_rows(const int wv_, KPR p, int l, int src_layer, const float* gvec, int part_shift, int part_scale, bool copy_ctx) {
;     ...
;     f32x4 v[8]; float ss = 0.f;
; #pragma unroll
;     for (int j = 0; j < 8; ++j) { v[j] = *(const f32x4*)(x + lane * 4 + 256 * j); ss += v[j][0] * v[j][0] + v[j][1] * v[j][1] + v[j][2] * v[j][2] + v[j][3] * v[j][3]; }
;     const float rstd = rsqrtf(wave_sum(ss) * (1.f / D) + 1e-6f);
	v_pk_add_f32 v[88:89], v[88:89], v[120:121]
	v_pk_add_f32 v[90:91], v[90:91], v[122:123]
	v_pk_add_f32 v[92:93], v[92:93], v[124:125]
	v_pk_add_f32 v[94:95], v[94:95], v[126:127]
	v_pk_add_f32 v[96:97], v[96:97], v[128:129]
	v_pk_add_f32 v[98:99], v[98:99], v[130:131]
	v_pk_add_f32 v[100:101], v[100:101], v[132:133]
	v_pk_add_f32 v[102:103], v[102:103], v[134:135]
	v_pk_add_f32 v[104:105], v[104:105], v[136:137]
	v_pk_add_f32 v[106:107], v[106:107], v[138:139]
	v_pk_add_f32 v[108:109], v[108:109], v[140:141]
	v_pk_add_f32 v[110:111], v[110:111], v[142:143]
	v_pk_add_f32 v[112:113], v[112:113], v[144:145]
	v_pk_add_f32 v[114:115], v[114:115], v[146:147]
	v_pk_add_f32 v[116:117], v[116:117], v[148:149]
	v_pk_add_f32 v[118:119], v[118:119], v[150:151]
	v_pk_add_f32 v[88:89], v[88:89], v[190:191]
	v_pk_add_f32 v[90:91], v[90:91], v[192:193]
	v_pk_add_f32 v[92:93], v[92:93], v[194:195]
	v_pk_add_f32 v[94:95], v[94:95], v[196:197]
	v_pk_add_f32 v[96:97], v[96:97], v[198:199]
	v_pk_add_f32 v[98:99], v[98:99], v[200:201]
	v_pk_add_f32 v[100:101], v[100:101], v[202:203]
	v_pk_add_f32 v[102:103], v[102:103], v[204:205]
	v_pk_add_f32 v[104:105], v[104:105], v[206:207]
	v_pk_add_f32 v[106:107], v[106:107], v[208:209]
	v_pk_add_f32 v[108:109], v[108:109], v[210:211]
	v_pk_add_f32 v[110:111], v[110:111], v[212:213]
	v_pk_add_f32 v[112:113], v[112:113], v[214:215]
	v_pk_add_f32 v[114:115], v[114:115], v[216:217]
	v_pk_add_f32 v[116:117], v[116:117], v[218:219]
	v_pk_add_f32 v[118:119], v[118:119], v[220:221]
	global_load_dwordx4 v[120:123], v[222:223], off
	global_load_dwordx4 v[124:127], v[222:223], off offset:1024
	global_load_dwordx4 v[128:131], v[222:223], off offset:2048
	global_load_dwordx4 v[132:135], v[222:223], off offset:3072
	global_load_dwordx4 v[136:139], v[224:225], off
	global_load_dwordx4 v[140:143], v[224:225], off offset:1024
	global_load_dwordx4 v[144:147], v[224:225], off offset:2048
	global_load_dwordx4 v[148:151], v[224:225], off offset:3072
	v_lshl_add_u64 v[222:223], v[222:223], 0, s[24:25]
	v_lshl_add_u64 v[224:225], v[224:225], 0, s[24:25]
	global_load_dwordx4 v[190:193], v[222:223], off
	global_load_dwordx4 v[194:197], v[222:223], off offset:1024
	global_load_dwordx4 v[198:201], v[222:223], off offset:2048
	global_load_dwordx4 v[202:205], v[222:223], off offset:3072
	global_load_dwordx4 v[206:209], v[224:225], off
	global_load_dwordx4 v[210:213], v[224:225], off offset:1024
	global_load_dwordx4 v[214:217], v[224:225], off offset:2048
	global_load_dwordx4 v[218:221], v[224:225], off offset:3072
	v_lshl_add_u64 v[222:223], v[222:223], 0, s[24:25]
	v_lshl_add_u64 v[224:225], v[224:225], 0, s[24:25]
	s_waitcnt vmcnt(0)
	v_pk_add_f32 v[88:89], v[88:89], v[120:121]
	v_pk_add_f32 v[90:91], v[90:91], v[122:123]
	v_pk_add_f32 v[92:93], v[92:93], v[124:125]
	v_pk_add_f32 v[94:95], v[94:95], v[126:127]
	v_pk_add_f32 v[96:97], v[96:97], v[128:129]
	v_pk_add_f32 v[98:99], v[98:99], v[130:131]
	v_pk_add_f32 v[100:101], v[100:101], v[132:133]
	v_pk_add_f32 v[102:103], v[102:103], v[134:135]
	v_pk_add_f32 v[104:105], v[104:105], v[136:137]
	v_pk_add_f32 v[106:107], v[106:107], v[138:139]
	v_pk_add_f32 v[108:109], v[108:109], v[140:141]
	v_pk_add_f32 v[110:111], v[110:111], v[142:143]
	v_pk_add_f32 v[112:113], v[112:113], v[144:145]
	v_pk_add_f32 v[114:115], v[114:115], v[146:147]
	v_pk_add_f32 v[116:117], v[116:117], v[148:149]
	v_pk_add_f32 v[118:119], v[118:119], v[150:151]
	v_pk_add_f32 v[88:89], v[88:89], v[190:191]
	v_pk_add_f32 v[90:91], v[90:91], v[192:193]
	v_pk_add_f32 v[92:93], v[92:93], v[194:195]
	v_pk_add_f32 v[94:95], v[94:95], v[196:197]
	v_pk_add_f32 v[96:97], v[96:97], v[198:199]
	v_pk_add_f32 v[98:99], v[98:99], v[200:201]
	v_pk_add_f32 v[100:101], v[100:101], v[202:203]
	v_pk_add_f32 v[102:103], v[102:103], v[204:205]
	v_pk_add_f32 v[104:105], v[104:105], v[206:207]
	v_pk_add_f32 v[106:107], v[106:107], v[208:209]
	v_pk_add_f32 v[108:109], v[108:109], v[210:211]
	v_pk_add_f32 v[110:111], v[110:111], v[212:213]
	v_pk_add_f32 v[112:113], v[112:113], v[214:215]
	v_pk_add_f32 v[114:115], v[114:115], v[216:217]
	v_pk_add_f32 v[116:117], v[116:117], v[218:219]
	v_pk_add_f32 v[118:119], v[118:119], v[220:221]
	global_load_dwordx4 v[120:123], v[222:223], off
	global_load_dwordx4 v[124:127], v[222:223], off offset:1024
	global_load_dwordx4 v[128:131], v[222:223], off offset:2048
	global_load_dwordx4 v[132:135], v[222:223], off offset:3072
	global_load_dwordx4 v[136:139], v[224:225], off
	global_load_dwordx4 v[140:143], v[224:225], off offset:1024
	global_load_dwordx4 v[144:147], v[224:225], off offset:2048
	global_load_dwordx4 v[148:151], v[224:225], off offset:3072
	global_load_dwordx4 v[190:193], v[226:227], off
	global_load_dwordx4 v[194:197], v[226:227], off offset:1024
	global_load_dwordx4 v[198:201], v[226:227], off offset:2048
	global_load_dwordx4 v[202:205], v[226:227], off offset:3072
	global_load_dwordx4 v[206:209], v[228:229], off
	global_load_dwordx4 v[210:213], v[228:229], off offset:1024
	global_load_dwordx4 v[214:217], v[228:229], off offset:2048
	global_load_dwordx4 v[218:221], v[228:229], off offset:3072
	s_waitcnt vmcnt(0)
	v_pk_add_f32 v[88:89], v[88:89], v[120:121]
	v_pk_add_f32 v[90:91], v[90:91], v[122:123]
	v_pk_add_f32 v[92:93], v[92:93], v[124:125]
	v_pk_add_f32 v[94:95], v[94:95], v[126:127]
	v_pk_add_f32 v[96:97], v[96:97], v[128:129]
	v_pk_add_f32 v[98:99], v[98:99], v[130:131]
	v_pk_add_f32 v[100:101], v[100:101], v[132:133]
	v_pk_add_f32 v[102:103], v[102:103], v[134:135]
	v_pk_add_f32 v[104:105], v[104:105], v[136:137]
	v_pk_add_f32 v[106:107], v[106:107], v[138:139]
	v_pk_add_f32 v[108:109], v[108:109], v[140:141]
	v_pk_add_f32 v[110:111], v[110:111], v[142:143]
	v_pk_add_f32 v[112:113], v[112:113], v[144:145]
	v_pk_add_f32 v[114:115], v[114:115], v[146:147]
	v_pk_add_f32 v[116:117], v[116:117], v[148:149]
	v_pk_add_f32 v[118:119], v[118:119], v[150:151]
	v_pk_fma_f32 v[32:33], v[88:89], v[190:191], v[32:33]
	v_pk_fma_f32 v[34:35], v[90:91], v[192:193], v[34:35]
	v_pk_fma_f32 v[28:29], v[92:93], v[194:195], v[28:29]
	v_pk_fma_f32 v[30:31], v[94:95], v[196:197], v[30:31]
	v_pk_fma_f32 v[24:25], v[96:97], v[198:199], v[24:25]
	v_pk_fma_f32 v[26:27], v[98:99], v[200:201], v[26:27]
	v_pk_fma_f32 v[20:21], v[100:101], v[202:203], v[20:21]
	v_pk_fma_f32 v[22:23], v[102:103], v[204:205], v[22:23]
	v_pk_fma_f32 v[16:17], v[104:105], v[206:207], v[16:17]
	v_pk_fma_f32 v[18:19], v[106:107], v[208:209], v[18:19]
	v_pk_fma_f32 v[12:13], v[108:109], v[210:211], v[12:13]
	v_pk_fma_f32 v[14:15], v[110:111], v[212:213], v[14:15]
	v_pk_fma_f32 v[8:9], v[112:113], v[214:215], v[8:9]
	v_pk_fma_f32 v[10:11], v[114:115], v[216:217], v[10:11]
	v_pk_fma_f32 v[4:5], v[116:117], v[218:219], v[4:5]
	v_pk_fma_f32 v[6:7], v[118:119], v[220:221], v[6:7]
	v_mul_f32_e32 v53, v33, v33
; #define p (kparams())
; __device__ __forceinline__ void norm_rows(const int wv_, KPR p, int l, int src_layer, const float* gvec, int part_shift, int part_scale, bool copy_ctx) {
;     ...
; #pragma unroll
;     for (int j = 0; j < 8; ++j) { v[j] = *(const f32x4*)(x + lane * 4 + 256 * j); ss += v[j][0] * v[j][0] + v[j][1] * v[j][1] + v[j][2] * v[j][2] + v[j][3] * v[j][3]; }
;     const float rstd = rsqrtf(wave_sum(ss) * (1.f / D) + 1e-6f);
;     if (copy_ctx && row_who(row) == 4) { float* xd = xrow_dst(p, row);
; #pragma unroll
;       for (int j = 0; j < 8; ++j) *(f32x4*)(xd + lane * 4 + 256 * j) = v[j]; }
.Lnr_skip:
	s_waitcnt vmcnt(6)
	v_mul_f32_e32 v55, v29, v29
	s_waitcnt vmcnt(5)
	v_mul_f32_e32 v57, v25, v25
	v_fmac_f32_e32 v53, v32, v32
	v_fmac_f32_e32 v55, v28, v28
	s_waitcnt vmcnt(4)
	v_mul_f32_e32 v59, v21, v21
	v_fmac_f32_e32 v57, v24, v24
	v_fmac_f32_e32 v53, v34, v34
	v_fmac_f32_e32 v55, v30, v30
	v_fmac_f32_e32 v59, v20, v20
	v_fmac_f32_e32 v57, v26, v26
	v_fmac_f32_e32 v53, v35, v35
	v_fmac_f32_e32 v55, v31, v31
	v_fmac_f32_e32 v59, v22, v22
	v_fmac_f32_e32 v57, v27, v27
	v_add_f32_e32 v53, v53, v55
	v_fmac_f32_e32 v59, v23, v23
	v_add_f32_e32 v53, v53, v57
	v_add_f32_e32 v53, v53, v59
	v_cmp_eq_u32_e32 vcc, 4, v3
	s_and_b64 s[22:23], s[6:7], vcc
	s_waitcnt vmcnt(3)
	v_mov_b32_e32 v68, v17
	s_waitcnt vmcnt(2)
	v_mov_b32_e32 v69, v13
	v_mov_b32_e32 v64, v16
	v_mov_b32_e32 v65, v12
	v_pk_mul_f32 v[68:69], v[68:69], v[68:69]
	v_mov_b32_e32 v70, v18
	v_mov_b32_e32 v71, v14
	s_waitcnt vmcnt(1)
	v_mov_b32_e32 v76, v9
	s_waitcnt vmcnt(0)
	v_mov_b32_e32 v77, v5
	v_pk_fma_f32 v[64:65], v[64:65], v[64:65], v[68:69]
	v_mov_b32_e32 v72, v19
	v_mov_b32_e32 v73, v15
	v_mov_b32_e32 v74, v8
	v_mov_b32_e32 v75, v4
	v_pk_mul_f32 v[76:77], v[76:77], v[76:77]
	v_pk_fma_f32 v[64:65], v[70:71], v[70:71], v[64:65]
	v_mov_b32_e32 v78, v10
	v_mov_b32_e32 v79, v6
	v_pk_fma_f32 v[68:69], v[74:75], v[74:75], v[76:77]
	v_pk_fma_f32 v[64:65], v[72:73], v[72:73], v[64:65]
	v_mov_b32_e32 v80, v11
	v_mov_b32_e32 v81, v7
	v_pk_fma_f32 v[68:69], v[78:79], v[78:79], v[68:69]
	v_add_f32_e32 v53, v53, v64
	v_add_f32_e32 v53, v53, v65
	v_pk_fma_f32 v[64:65], v[80:81], v[80:81], v[68:69]
	s_nop 0
	v_add_f32_e32 v53, v53, v64
	v_add_f32_e32 v53, v53, v65
	ds_bpermute_b32 v55, v170, v53
	s_waitcnt lgkmcnt(0)
	v_add_f32_e32 v53, v53, v55
	ds_bpermute_b32 v55, v171, v53
	s_waitcnt lgkmcnt(0)
	v_add_f32_e32 v53, v53, v55
	ds_bpermute_b32 v55, v172, v53
	s_waitcnt lgkmcnt(0)
	v_add_f32_e32 v53, v53, v55
	ds_bpermute_b32 v55, v173, v53
	s_waitcnt lgkmcnt(0)
	v_add_f32_e32 v53, v53, v55
	ds_bpermute_b32 v55, v174, v53
	s_waitcnt lgkmcnt(0)
	v_add_f32_e32 v53, v53, v55
	ds_bpermute_b32 v55, v175, v53
	s_and_saveexec_b64 s[20:21], s[22:23]
	s_cbranch_execz .LBB0_131
	s_and_saveexec_b64 s[24:25], s[4:5]
	s_xor_b64 s[4:5], exec, s[24:25]
	s_load_dwordx2 s[22:23], s[10:11], 0x110
	v_lshl_add_u32 v1, v1, 12, v51
	v_add3_u32 v64, v0, v1, s89
	s_or_saveexec_b64 s[4:5], s[4:5]
	s_waitcnt lgkmcnt(0)
	v_mov_b64_e32 v[68:69], s[22:23]
	s_xor_b64 exec, exec, s[4:5]
	s_cbranch_execz .LBB0_130
	v_lshl_add_u32 v64, v1, 8, v37
	v_mov_b64_e32 v[68:69], s[16:17]
	s_branch .LBB0_130

; #define ws (kparams()->ws)
;   __device__ bool tile(long L, int& pm, int& pn) const {
;     if (L >= nwg) return false;
;     int wgid = (int)L; { const int q = nwg / NXCD, r = nwg % NXCD, xcd = wgid % NXCD, off = wgid / NXCD; wgid = (xcd < r ? xcd * (q + 1) : r * (q + 1) + (xcd - r) * q) + off; }
;     const int nig = WGM * nN, gid = wgid / nig, fm = gid * WGM, gsz = (nM - fm) < WGM ? (nM - fm) : WGM;
;     pm = fm + ((wgid % nig) % gsz); pn = (wgid % nig) / gsz; if (lat) pm = (pm >> 4) * 17 + 1 + (pm & 15); return true;
; __global__ void __launch_bounds__(512, 2) fwd_megakernel(Params p_unused) {
;     ...
;     { g8::SchedSplit S; S.mode = l == 1 ? 1 : 0; S.o.init(T / 256, D / 256, S.mode != 0); S.nt = HID / 64; S.A = (const char*)(ws + WS_PG); S.B = (const char*)(ws + WS_W2); S.at = (size_t)256 * HID * 2; S.bt = (size_t)256 * HID * 2;
;       g8::EpiResid E{1, modl, 5};
.LBB0_1232:
	s_or_b64 exec, exec, s[8:9]
	s_mov_b64 s[8:9], s[0:1]
	s_waitcnt lgkmcnt(0)
	s_barrier
	s_load_dwordx2 s[8:9], s[8:9], 0x118
	s_mov_b64 s[10:11], s[0:1]
	s_load_dwordx2 s[10:11], s[10:11], 0x118
	v_mov_b32_e32 v4, v153
	s_waitcnt lgkmcnt(0)
	s_add_u32 s34, s8, 0x192e0000
	s_addc_u32 s35, s9, 0
	s_add_u32 s36, s10, 0x40e0000
	v_or_b32_e32 v0, s72, v4
	s_addc_u32 s37, s11, 0
	s_and_b64 vcc, exec, s[6:7]
	v_readfirstlane_b32 s38, v0
	v_readlane_b32 s8, v242, 59
	s_cmp_eq_u32 s8, 0
	s_cselect_b32 s8, 1, 0
	s_cmp_eq_u32 s33, 0x100
	s_cselect_b32 s8, s8, 0
	v_writelane_b32 v242, s8, 62
	s_cmp_lg_u32 s8, 0
	s_cbranch_scc0 .Lg5s_nomode
	s_mov_b32 s53, 64
	s_mov_b32 s14, 0x200
	s_mov_b64 s[4:5], 0
.Lg5s_nomode:
	s_cbranch_vccnz .LBB0_1236
	v_readlane_b32 s8, v242, 41
	s_or_b32 s8, s53, s8
	v_readlane_b32 s9, v242, 40
	s_mul_i32 s8, s8, s9
	v_readlane_b32 s9, v242, 30
	s_add_i32 s8, s8, s9
	s_ashr_i32 s9, s8, 31
	s_lshr_b32 s9, s9, 27
	s_add_i32 s9, s8, s9
	s_ashr_i32 s10, s9, 5
	s_lshl_b32 s10, s10, 2
	s_sub_i32 s11, s53, s10
	s_min_i32 s11, s11, 4
	s_abs_i32 s12, s11
	v_cvt_f32_u32_e32 v1, s12
	s_sub_i32 s15, 0, s12
	s_andn2_b32 s9, s9, 31
	s_sub_i32 s8, s8, s9
	v_rcp_iflag_f32_e32 v1, v1
	s_abs_i32 s9, s8
	s_xor_b32 s13, s8, s11
	s_ashr_i32 s13, s13, 31
	v_mul_f32_e32 v1, 0x4f7ffffe, v1
	v_cvt_u32_f32_e32 v1, v1
	s_nop 0
	v_readfirstlane_b32 s16, v1
	s_mul_i32 s15, s15, s16
	s_mul_hi_u32 s15, s16, s15
	s_add_i32 s16, s16, s15
	s_mul_hi_u32 s15, s9, s16
	s_mul_i32 s16, s15, s12
	s_sub_i32 s9, s9, s16
	s_add_i32 s17, s15, 1
	s_sub_i32 s16, s9, s12
	s_cmp_ge_u32 s9, s12
	s_cselect_b32 s15, s17, s15
	s_cselect_b32 s9, s16, s9
	s_add_i32 s16, s15, 1
	s_cmp_ge_u32 s9, s12
	s_cselect_b32 s9, s16, s15
	s_xor_b32 s9, s9, s13
	s_sub_i32 s18, s9, s13
	s_mul_i32 s9, s18, s11
	s_sub_i32 s8, s8, s9
	s_and_b64 vcc, exec, s[4:5]
	s_add_i32 s20, s10, s8
	s_cbranch_vccnz .LBB0_1235
	s_ashr_i32 s8, s20, 4
	s_mul_i32 s8, s8, 17
	s_and_b32 s9, s20, 15
	s_add_i32 s8, s9, s8
	s_add_i32 s20, s8, 1

;   __device__ bool next(int i, Unit& u) const {
;     if (mode == 2 && i >= 2) { if (i > 2) return false;
;       const int ct = o.c >> 3, ks = o.c & 7, pm = (ct >> 3) * 17, pn = ct & 7;
;       u.pm = pm; u.pn = pn; u.j = 0; u.nt = nt >> 3; u.split = 1; u.a = A + (size_t)pm * at + (size_t)ks * (nt >> 3) * 128; u.b = B + (size_t)pn * bt + (size_t)ks * (nt >> 3) * 128; return true; }
.Lg5s_sched:
	s_lshr_b32 s8, s2, 3
	s_and_b32 s9, s2, 7
	s_lshr_b32 s10, s8, 3
	s_mul_i32 s10, s10, 17
	s_and_b32 s8, s8, 7
	s_lshl_b32 s9, s9, 11
	s_lshl_b32 s11, s10, 22
	s_add_u32 s12, s34, s11
	s_addc_u32 s13, s35, 0
	s_add_u32 s12, s12, s9
	s_addc_u32 s13, s13, 0
	s_lshl_b32 s11, s8, 22
	s_add_u32 s16, s36, s11
	s_addc_u32 s17, s37, 0
	s_add_u32 s16, s16, s9
	s_addc_u32 s17, s17, 0
	s_mov_b64 s[22:23], s[12:13]
	s_mov_b64 s[24:25], s[16:17]
	s_mov_b64 s[6:7], 0
	s_branch .LBB0_1245

;   __device__ bool tile(long L, int& pm, int& pn) const {
;     if (L >= nwg) return false;
;     int wgid = (int)L; { const int q = nwg / NXCD, r = nwg % NXCD, xcd = wgid % NXCD, off = wgid / NXCD; wgid = (xcd < r ? xcd * (q + 1) : r * (q + 1) + (xcd - r) * q) + off; }
;     const int nig = WGM * nN, gid = wgid / nig, fm = gid * WGM, gsz = (nM - fm) < WGM ? (nM - fm) : WGM;
;     pm = fm + ((wgid % nig) % gsz); pn = (wgid % nig) / gsz; if (lat) pm = (pm >> 4) * 17 + 1 + (pm & 15); return true;
;   __device__ bool next(int i, Unit& u) const {
;     if (mode == 2 && i >= 2) { if (i > 2) return false;
;       const int ct = o.c >> 3, ks = o.c & 7, pm = (ct >> 3) * 17, pn = ct & 7;
;       u.pm = pm; u.pn = pn; u.j = 0; u.nt = nt >> 3; u.split = 1; u.a = A + (size_t)pm * at + (size_t)ks * (nt >> 3) * 128; u.b = B + (size_t)pn * bt + (size_t)ks * (nt >> 3) * 128; return true; }
;     int pm, pn; if (!o.tile((long)i * o.G + o.c, pm, pn)) return false; u.pm = pm; u.pn = pn; u.j = 0; u.nt = nt; u.split = 0; u.a = A + (size_t)pm * at; u.b = B + (size_t)pn * bt; return true; }
.LBB0_1241:
	s_add_i32 s50, s50, 1
	s_mul_i32 s6, s50, s79
	s_mul_hi_u32 s7, s50, s33
	s_add_i32 s7, s7, s6
	s_mul_i32 s6, s50, s33
	s_add_u32 s30, s6, s2
	s_addc_u32 s31, s7, s44
	v_mov_b64_e32 v[4:5], s[14:15]
	v_cmp_ge_i64_e64 s[6:7], s[30:31], v[4:5]
	v_readlane_b32 s8, v242, 62
	s_cmp_eq_u32 s50, 2
	s_cselect_b32 s8, s8, 0
	s_cmp_lg_u32 s8, 0
	s_cbranch_scc1 .Lg5s_sched
	s_and_b64 vcc, exec, s[6:7]
	s_mov_b64 s[22:23], s[26:27]
	s_mov_b64 s[24:25], s[28:29]
	s_cbranch_vccnz .LBB0_1245
	s_ashr_i32 s8, s30, 31
	s_lshr_b32 s8, s8, 29
	s_add_i32 s8, s30, s8
	s_ashr_i32 s9, s8, 3
	s_and_b32 s8, s8, -8
	s_sub_i32 s8, s30, s8
	s_lshr_b32 s10, s8, 31
	s_or_b32 s10, s53, s10
	s_mul_i32 s8, s10, s8
	s_add_i32 s8, s8, s9
	s_ashr_i32 s9, s8, 31
	s_lshr_b32 s9, s9, 27
	s_add_i32 s9, s8, s9
	s_ashr_i32 s10, s9, 5
	s_lshl_b32 s10, s10, 2
	s_sub_i32 s11, s53, s10
	s_min_i32 s11, s11, 4
	s_abs_i32 s12, s11
	v_cvt_f32_u32_e32 v4, s12
	s_sub_i32 s16, 0, s12
	s_andn2_b32 s9, s9, 31
	s_sub_i32 s9, s8, s9
	v_rcp_iflag_f32_e32 v4, v4
	s_abs_i32 s8, s9
	s_xor_b32 s13, s9, s11
	s_ashr_i32 s13, s13, 31
	v_mul_f32_e32 v4, 0x4f7ffffe, v4
	v_cvt_u32_f32_e32 v4, v4
	s_nop 0
	v_readfirstlane_b32 s17, v4
	s_mul_i32 s16, s16, s17
	s_mul_hi_u32 s16, s17, s16
	s_add_i32 s17, s17, s16
	s_mul_hi_u32 s16, s8, s17
	s_mul_i32 s17, s16, s12
	s_sub_i32 s8, s8, s17
	s_add_i32 s19, s16, 1
	s_sub_i32 s17, s8, s12
	s_cmp_ge_u32 s8, s12
	s_cselect_b32 s16, s19, s16
	s_cselect_b32 s8, s17, s8
	s_add_i32 s17, s16, 1
	s_cmp_ge_u32 s8, s12
	s_cselect_b32 s8, s17, s16
	s_xor_b32 s8, s8, s13
	s_sub_i32 s8, s8, s13
	s_mul_i32 s11, s8, s11
	s_sub_i32 s9, s9, s11
	s_and_b64 vcc, exec, s[4:5]
	s_add_i32 s10, s9, s10
	s_cbranch_vccnz .LBB0_1244
	s_ashr_i32 s9, s10, 4
	s_mul_i32 s9, s9, 17
	s_and_b32 s10, s10, 15
	s_add_i32 s9, s10, s9
	s_add_i32 s10, s9, 1

; #define G8_STAGE(bufoff, gbase, voff) do { _Pragma("unroll") for (int _i = 0; _i < 2; ++_i) \
;     __builtin_amdgcn_global_load_lds((const unsigned*)((const char*)(gbase) + (voff)[_i]), (LAS unsigned*)(lds + (bufoff) + ldsw + _i * 8192), 16, 0, 0); } while (0)
; #define G8_LDA(dst, b, h) do { _Pragma("unroll") for (int m = 0; m < 4; ++m) _Pragma("unroll") for (int k = 0; k < 2; ++k) dst[m][k] = *(const LAS bf16x8*)(lds + G8_SA(b, h) + aoff + m * 2048 + k * 1024); } while (0)
; #define G8_LDB(dst, b, h) do { _Pragma("unroll") for (int n = 0; n < 2; ++n) _Pragma("unroll") for (int k = 0; k < 2; ++k) dst[n][k] = *(const LAS bf16x8*)(lds + G8_SB(b, h) + boff + n * 2048 + k * 1024); } while (0)
; #define G8_BAR __builtin_amdgcn_s_barrier()
; template <class Epi, class Sched>
; __device__ __forceinline__ void gemm_phase(const int wv_, LAS unsigned char* lds, const int lda, const int ldb, const int K, const Sched& S, const Epi& E) {
;     ...
;   f32x4 acc[2][2][4][2];
; #pragma unroll
;   for (int a = 0; a < 2; ++a)
; #pragma unroll
;     for (int b = 0; b < 2; ++b)
; #pragma unroll
;       for (int m = 0; m < 4; ++m)
; #pragma unroll
;         for (int n = 0; n < 2; ++n) acc[a][b][m][n] = (f32x4){0.f, 0.f, 0.f, 0.f};
;   bf16x8 At[4][2], B0[2][2], B1[2][2];
;   const char* cA = cur.a; const char* cB = cur.b;
;   G8_STAGE(G8_SB(0, 0), cB, voffB); G8_STAGE(G8_SA(0, 0), cA, voffA); G8_STAGE(G8_SB(0, 1), cB + hstepB, voffB); G8_STAGE(G8_SA(0, 1), cA + hstepA, voffA);
;   if (wr == 1) G8_BAR;
;   G8_WAIT_V(4); G8_BAR;
;   G8_STAGE(G8_SB(1, 0), cB + kstep, voffB); G8_STAGE(G8_SA(1, 0), cA + kstep, voffA); G8_STAGE(G8_SB(1, 1), cB + hstepB + kstep, voffB);
;   G8_WAIT_V(6); G8_BAR;
;   for (;;) {
;     const bool has_next = S.next(ui + 1, nxt);
;     const char* nA = has_next ? nxt.a : cA; const char* nB = has_next ? nxt.b : cB;
;     const int nt = cur.nt;
;     for (int t = 0; t < nt; t += 2) {
;       const bool last = (t == nt - 2);
;       const char* a1 = cA + (size_t)(t + 1) * kstep;
;       const char* a2 = last ? nA : cA + (size_t)(t + 2) * kstep; const char* b2 = last ? nB : cB + (size_t)(t + 2) * kstep;
;       const char* a3 = a2 + kstep; const char* b3 = b2 + kstep;
;       G8_LDB(B0, 0, 0); G8_SCHED; G8_LDA(At, 0, 0); G8_STAGE(G8_SA(1, 1), a1 + hstepA, voffA);
;       G8_WAIT_L(8); G8_BAR; G8_WAIT_L(0); G8_MMA(0, 0, At, B0); G8_BAR; G8_SCHED;
.LBB0_1245:
	s_add_u32 s26, s26, 0x200080
	s_addc_u32 s27, s27, 0
	s_add_u32 s9, s28, 0x100
	v_mov_b32_e32 v4, 0
	s_addc_u32 s11, s29, 0
	v_readlane_b32 s19, v242, 62
	s_cmp_eq_u32 s50, 3
	s_cselect_b32 s19, s19, 0
	s_cmp_lg_u32 s19, 0
	s_cselect_b32 s19, 0x6e, -2
	v_mov_b32_e32 v5, v4
	v_mov_b32_e32 v6, v4
	v_mov_b32_e32 v7, v4
	v_mov_b32_e32 v8, v4
	v_mov_b32_e32 v9, v4
	v_mov_b32_e32 v10, v4
	v_mov_b32_e32 v11, v4
	v_mov_b32_e32 v20, v4
	v_mov_b32_e32 v21, v4
	v_mov_b32_e32 v22, v4
	v_mov_b32_e32 v23, v4
	v_mov_b32_e32 v24, v4
	v_mov_b32_e32 v25, v4
	v_mov_b32_e32 v26, v4
	v_mov_b32_e32 v27, v4
	v_mov_b32_e32 v36, v4
	v_mov_b32_e32 v37, v4
	v_mov_b32_e32 v38, v4
	v_mov_b32_e32 v39, v4
	v_mov_b32_e32 v40, v4
	v_mov_b32_e32 v41, v4
	v_mov_b32_e32 v42, v4
	v_mov_b32_e32 v43, v4
	v_mov_b32_e32 v52, v4
	v_mov_b32_e32 v53, v4
	v_mov_b32_e32 v54, v4
	v_mov_b32_e32 v55, v4
	v_mov_b32_e32 v56, v4
	v_mov_b32_e32 v57, v4
	v_mov_b32_e32 v58, v4
	v_mov_b32_e32 v59, v4
	v_mov_b32_e32 v12, v4
	v_mov_b32_e32 v13, v4
	v_mov_b32_e32 v14, v4
	v_mov_b32_e32 v15, v4
	v_mov_b32_e32 v16, v4
	v_mov_b32_e32 v17, v4
	v_mov_b32_e32 v18, v4
	v_mov_b32_e32 v19, v4
	v_mov_b32_e32 v28, v4
	v_mov_b32_e32 v29, v4
	v_mov_b32_e32 v30, v4
	v_mov_b32_e32 v31, v4
	v_mov_b32_e32 v32, v4
	v_mov_b32_e32 v33, v4
	v_mov_b32_e32 v34, v4
	v_mov_b32_e32 v35, v4
	v_mov_b32_e32 v44, v4
	v_mov_b32_e32 v45, v4
	v_mov_b32_e32 v46, v4
	v_mov_b32_e32 v47, v4
	v_mov_b32_e32 v48, v4
	v_mov_b32_e32 v49, v4
	v_mov_b32_e32 v50, v4
	v_mov_b32_e32 v51, v4
	v_mov_b32_e32 v60, v4
	v_mov_b32_e32 v61, v4
	v_mov_b32_e32 v62, v4
	v_mov_b32_e32 v63, v4
	v_mov_b32_e32 v64, v4
	v_mov_b32_e32 v65, v4
	v_mov_b32_e32 v66, v4
	v_mov_b32_e32 v67, v4
	v_mov_b32_e32 v84, v4
	v_mov_b32_e32 v85, v4
	v_mov_b32_e32 v86, v4
	v_mov_b32_e32 v87, v4
	v_mov_b32_e32 v88, v4
	v_mov_b32_e32 v89, v4
	v_mov_b32_e32 v90, v4
	v_mov_b32_e32 v91, v4
	v_mov_b32_e32 v100, v4
	v_mov_b32_e32 v101, v4
	v_mov_b32_e32 v102, v4
	v_mov_b32_e32 v103, v4
	v_mov_b32_e32 v104, v4
	v_mov_b32_e32 v105, v4
	v_mov_b32_e32 v106, v4
	v_mov_b32_e32 v107, v4
	v_mov_b32_e32 v116, v4
	v_mov_b32_e32 v117, v4
	v_mov_b32_e32 v118, v4
	v_mov_b32_e32 v119, v4
	v_mov_b32_e32 v120, v4
	v_mov_b32_e32 v121, v4
	v_mov_b32_e32 v122, v4
	v_mov_b32_e32 v123, v4
	v_mov_b32_e32 v132, v4
	v_mov_b32_e32 v133, v4
	v_mov_b32_e32 v134, v4
	v_mov_b32_e32 v135, v4
	v_mov_b32_e32 v136, v4
	v_mov_b32_e32 v137, v4
	v_mov_b32_e32 v138, v4
	v_mov_b32_e32 v139, v4
	v_mov_b32_e32 v92, v4
	v_mov_b32_e32 v93, v4
	v_mov_b32_e32 v94, v4
	v_mov_b32_e32 v95, v4
	v_mov_b32_e32 v96, v4
	v_mov_b32_e32 v97, v4
	v_mov_b32_e32 v98, v4
	v_mov_b32_e32 v99, v4
	v_mov_b32_e32 v108, v4
	v_mov_b32_e32 v109, v4
	v_mov_b32_e32 v110, v4
	v_mov_b32_e32 v111, v4
	v_mov_b32_e32 v112, v4
	v_mov_b32_e32 v113, v4
	v_mov_b32_e32 v114, v4
	v_mov_b32_e32 v115, v4
	v_mov_b32_e32 v124, v4
	v_mov_b32_e32 v125, v4
	v_mov_b32_e32 v126, v4
	v_mov_b32_e32 v127, v4
	v_mov_b32_e32 v128, v4
	v_mov_b32_e32 v129, v4
	v_mov_b32_e32 v130, v4
	v_mov_b32_e32 v131, v4
	v_mov_b32_e32 v140, v4
	v_mov_b32_e32 v141, v4
	v_mov_b32_e32 v142, v4
	v_mov_b32_e32 v143, v4
	v_mov_b32_e32 v144, v4
	v_mov_b32_e32 v145, v4
	v_mov_b32_e32 v146, v4
	v_mov_b32_e32 v147, v4
.LBB0_1246:
	s_add_u32 s21, s26, 0xffe00080
	s_addc_u32 s28, s27, -1
	s_add_i32 s51, 0, 0x10000
	v_add_u32_e32 v80, s51, v168
	ds_read_b128 v[68:71], v80
	ds_read_b128 v[72:75], v80 offset:1024
	ds_read_b128 v[76:79], v80 offset:2048
	ds_read_b128 v[80:83], v80 offset:3072
	s_cmpk_eq_i32 s19, 0x7c
	s_cselect_b32 s31, s23, s28
	s_cselect_b32 s30, s22, s21
	s_cselect_b32 s29, s25, s11
	s_cselect_b32 s28, s24, s9
	v_lshl_add_u64 v[166:167], s[26:27], 0, v[150:151]
	s_add_i32 m0, s40, 0xc000
	ds_read_b128 v[158:161], v189
	ds_read_b128 v[162:165], v189 offset:1024
	ds_read_b128 v[190:193], v189 offset:2048
	ds_read_b128 v[194:197], v189 offset:3072
	ds_read_b128 v[198:201], v189 offset:4096
	ds_read_b128 v[202:205], v189 offset:5120
	ds_read_b128 v[206:209], v189 offset:6144
	ds_read_b128 v[210:213], v189 offset:7168
	global_load_lds_dwordx4 v[166:167], off
	v_lshl_add_u64 v[166:167], s[26:27], 0, v[156:157]
	s_add_i32 m0, s40, 0xe000
	s_nop 0
	global_load_lds_dwordx4 v[166:167], off
	s_waitcnt lgkmcnt(8)
	s_barrier
	s_waitcnt lgkmcnt(0)
	s_setprio 1
	s_waitcnt lgkmcnt(0)
	v_mfma_f32_16x16x32_bf16 v[144:147], v[68:71], v[158:161], v[144:147]
	v_mfma_f32_16x16x32_bf16 v[140:143], v[76:79], v[158:161], v[140:143]
	v_mfma_f32_16x16x32_bf16 v[128:131], v[68:71], v[190:193], v[128:131]
	v_mfma_f32_16x16x32_bf16 v[124:127], v[76:79], v[190:193], v[124:127]
	v_mfma_f32_16x16x32_bf16 v[112:115], v[68:71], v[198:201], v[112:115]
	v_mfma_f32_16x16x32_bf16 v[108:111], v[76:79], v[198:201], v[108:111]
	v_mfma_f32_16x16x32_bf16 v[96:99], v[68:71], v[206:209], v[96:99]
	v_mfma_f32_16x16x32_bf16 v[92:95], v[76:79], v[206:209], v[92:95]
	v_mfma_f32_16x16x32_bf16 v[144:147], v[72:75], v[162:165], v[144:147]
	v_mfma_f32_16x16x32_bf16 v[140:143], v[80:83], v[162:165], v[140:143]
	v_mfma_f32_16x16x32_bf16 v[128:131], v[72:75], v[194:197], v[128:131]
	v_mfma_f32_16x16x32_bf16 v[124:127], v[80:83], v[194:197], v[124:127]
	v_mfma_f32_16x16x32_bf16 v[112:115], v[72:75], v[202:205], v[112:115]
	v_mfma_f32_16x16x32_bf16 v[108:111], v[80:83], v[202:205], v[108:111]
	v_mfma_f32_16x16x32_bf16 v[96:99], v[72:75], v[210:213], v[96:99]
	v_mfma_f32_16x16x32_bf16 v[92:95], v[80:83], v[210:213], v[92:95]
	s_setprio 0
	s_barrier
; #define G8_STAGE(bufoff, gbase, voff) do { _Pragma("unroll") for (int _i = 0; _i < 2; ++_i) \
;     __builtin_amdgcn_global_load_lds((const unsigned*)((const char*)(gbase) + (voff)[_i]), (LAS unsigned*)(lds + (bufoff) + ldsw + _i * 8192), 16, 0, 0); } while (0)
; #define G8_LDA(dst, b, h) do { _Pragma("unroll") for (int m = 0; m < 4; ++m) _Pragma("unroll") for (int k = 0; k < 2; ++k) dst[m][k] = *(const LAS bf16x8*)(lds + G8_SA(b, h) + aoff + m * 2048 + k * 1024); } while (0)
; #define G8_LDB(dst, b, h) do { _Pragma("unroll") for (int n = 0; n < 2; ++n) _Pragma("unroll") for (int k = 0; k < 2; ++k) dst[n][k] = *(const LAS bf16x8*)(lds + G8_SB(b, h) + boff + n * 2048 + k * 1024); } while (0)
; #define G8_MMA(ai, bj, At, Bt) do { __builtin_amdgcn_s_setprio(1); _Pragma("unroll") for (int m = 0; m < 4; ++m) _Pragma("unroll") for (int n = 0; n < 2; ++n) _Pragma("unroll") for (int k = 0; k < 2; ++k) \
;     acc[ai][bj][m][n] = __builtin_amdgcn_mfma_f32_16x16x32_bf16(Bt[n][k], At[m][k], acc[ai][bj][m][n], 0, 0, 0); __builtin_amdgcn_s_setprio(0); } while (0)
; #define G8_WAIT_V(n) asm volatile("s_waitcnt vmcnt(" #n ")" ::: "memory")
; #define G8_WAIT_L(n) asm volatile("s_waitcnt lgkmcnt(" #n ")" ::: "memory")
; #define G8_BAR __builtin_amdgcn_s_barrier()
; #define G8_SCHED __builtin_amdgcn_sched_barrier(0)
; template <class Epi, class Sched>
; __device__ __forceinline__ void gemm_phase(const int wv_, LAS unsigned char* lds, const int lda, const int ldb, const int K, const Sched& S, const Epi& E) {
;     ...
;       G8_LDB(B1, 0, 1); G8_STAGE(G8_SB(0, 0), b2, voffB);
;       G8_BAR; G8_WAIT_L(0); G8_MMA(0, 1, At, B1); G8_BAR;
;       G8_LDA(At, 0, 1); G8_STAGE(G8_SA(0, 0), a2, voffA);
;       G8_BAR; G8_WAIT_L(0); G8_MMA(1, 0, At, B0); G8_BAR; G8_SCHED;
;       G8_STAGE(G8_SB(0, 1), b2 + hstepB, voffB);
;       G8_WAIT_V(6); G8_BAR; G8_MMA(1, 1, At, B1); G8_BAR;
;       G8_LDB(B0, 1, 0); G8_SCHED; G8_LDA(At, 1, 0); G8_STAGE(G8_SA(0, 1), a2 + hstepA, voffA);
;       G8_WAIT_L(8); G8_BAR; G8_WAIT_L(0); G8_MMA(0, 0, At, B0); G8_BAR; G8_SCHED;
;       G8_LDB(B1, 1, 1); G8_STAGE(G8_SB(1, 0), b3, voffB);
;       G8_BAR; G8_WAIT_L(0); G8_MMA(0, 1, At, B1); G8_BAR;
;       G8_LDA(At, 1, 1); G8_STAGE(G8_SA(1, 0), a3, voffA);
	s_add_i32 s21, 0, 0x14000
	v_add_u32_e32 v166, s21, v168
	s_add_i32 s51, s51, s39
	ds_read_b128 v[214:217], v166
	ds_read_b128 v[218:221], v166 offset:1024
	ds_read_b128 v[222:225], v166 offset:2048
	ds_read_b128 v[226:229], v166 offset:3072
	v_lshl_add_u64 v[166:167], s[28:29], 0, v[0:1]
	s_mov_b32 m0, s51
	v_lshl_add_u64 v[230:231], s[28:29], 0, v[148:149]
	global_load_lds_dwordx4 v[166:167], off
	s_add_i32 m0, s51, 0x2000
	s_nop 0
	global_load_lds_dwordx4 v[230:231], off
	s_barrier
	s_waitcnt lgkmcnt(0)
	s_setprio 1
	s_waitcnt lgkmcnt(0)
	v_mfma_f32_16x16x32_bf16 v[136:139], v[214:217], v[158:161], v[136:139]
	v_mfma_f32_16x16x32_bf16 v[132:135], v[222:225], v[158:161], v[132:135]
	v_mfma_f32_16x16x32_bf16 v[120:123], v[214:217], v[190:193], v[120:123]
	v_mfma_f32_16x16x32_bf16 v[116:119], v[222:225], v[190:193], v[116:119]
	v_mfma_f32_16x16x32_bf16 v[104:107], v[214:217], v[198:201], v[104:107]
	v_mfma_f32_16x16x32_bf16 v[100:103], v[222:225], v[198:201], v[100:103]
	v_mfma_f32_16x16x32_bf16 v[88:91], v[214:217], v[206:209], v[88:91]
	v_mfma_f32_16x16x32_bf16 v[84:87], v[222:225], v[206:209], v[84:87]
	v_mfma_f32_16x16x32_bf16 v[136:139], v[218:221], v[162:165], v[136:139]
	v_mfma_f32_16x16x32_bf16 v[132:135], v[226:229], v[162:165], v[132:135]
	v_mfma_f32_16x16x32_bf16 v[120:123], v[218:221], v[194:197], v[120:123]
	v_mfma_f32_16x16x32_bf16 v[116:119], v[226:229], v[194:197], v[116:119]
	v_mfma_f32_16x16x32_bf16 v[104:107], v[218:221], v[202:205], v[104:107]
	v_mfma_f32_16x16x32_bf16 v[100:103], v[226:229], v[202:205], v[100:103]
	v_mfma_f32_16x16x32_bf16 v[88:91], v[218:221], v[210:213], v[88:91]
	v_mfma_f32_16x16x32_bf16 v[84:87], v[226:229], v[210:213], v[84:87]
	s_setprio 0
	s_mov_b32 m0, s40
	v_lshl_add_u64 v[232:233], s[30:31], 0, v[0:1]
	s_barrier
	ds_read_b128 v[158:161], v189 offset:16384
	ds_read_b128 v[162:165], v189 offset:17408
	ds_read_b128 v[190:193], v189 offset:18432
	ds_read_b128 v[194:197], v189 offset:19456
	ds_read_b128 v[198:201], v189 offset:20480
	ds_read_b128 v[202:205], v189 offset:21504
	ds_read_b128 v[206:209], v189 offset:22528
	ds_read_b128 v[210:213], v189 offset:23552
	global_load_lds_dwordx4 v[232:233], off
	v_lshl_add_u64 v[234:235], s[30:31], 0, v[148:149]
	s_mov_b32 m0, s41
	s_nop 0
	global_load_lds_dwordx4 v[234:235], off
	s_barrier
	s_waitcnt lgkmcnt(0)
	s_setprio 1
	s_waitcnt lgkmcnt(0)
	v_mfma_f32_16x16x32_bf16 v[64:67], v[68:71], v[158:161], v[64:67]
	v_mfma_f32_16x16x32_bf16 v[60:63], v[76:79], v[158:161], v[60:63]
	v_mfma_f32_16x16x32_bf16 v[48:51], v[68:71], v[190:193], v[48:51]
	v_mfma_f32_16x16x32_bf16 v[44:47], v[76:79], v[190:193], v[44:47]
	v_mfma_f32_16x16x32_bf16 v[32:35], v[68:71], v[198:201], v[32:35]
	v_mfma_f32_16x16x32_bf16 v[28:31], v[76:79], v[198:201], v[28:31]
	v_mfma_f32_16x16x32_bf16 v[16:19], v[68:71], v[206:209], v[16:19]
	v_mfma_f32_16x16x32_bf16 v[12:15], v[76:79], v[206:209], v[12:15]
	v_mfma_f32_16x16x32_bf16 v[64:67], v[72:75], v[162:165], v[64:67]
	v_mfma_f32_16x16x32_bf16 v[60:63], v[80:83], v[162:165], v[60:63]
	v_mfma_f32_16x16x32_bf16 v[48:51], v[72:75], v[194:197], v[48:51]
	v_mfma_f32_16x16x32_bf16 v[44:47], v[80:83], v[194:197], v[44:47]
	v_mfma_f32_16x16x32_bf16 v[32:35], v[72:75], v[202:205], v[32:35]
	v_mfma_f32_16x16x32_bf16 v[28:31], v[80:83], v[202:205], v[28:31]
	v_mfma_f32_16x16x32_bf16 v[16:19], v[72:75], v[210:213], v[16:19]
	v_mfma_f32_16x16x32_bf16 v[12:15], v[80:83], v[210:213], v[12:15]
	s_setprio 0
	s_barrier
	s_add_u32 s58, s28, 0x200000
	s_addc_u32 s59, s29, 0
	s_add_i32 s21, s21, s39
	v_lshl_add_u64 v[68:69], s[58:59], 0, v[0:1]
	s_mov_b32 m0, s21
	s_nop 0
	global_load_lds_dwordx4 v[68:69], off
	v_lshl_add_u64 v[68:69], s[58:59], 0, v[148:149]
	s_add_i32 m0, s21, 0x2000
	s_nop 0
	global_load_lds_dwordx4 v[68:69], off
	s_waitcnt vmcnt(6)
	s_barrier
	s_setprio 1
	v_mfma_f32_16x16x32_bf16 v[56:59], v[214:217], v[158:161], v[56:59]
	v_mfma_f32_16x16x32_bf16 v[52:55], v[222:225], v[158:161], v[52:55]
	v_mfma_f32_16x16x32_bf16 v[40:43], v[214:217], v[190:193], v[40:43]
	v_mfma_f32_16x16x32_bf16 v[36:39], v[222:225], v[190:193], v[36:39]
	v_mfma_f32_16x16x32_bf16 v[24:27], v[214:217], v[198:201], v[24:27]
	v_mfma_f32_16x16x32_bf16 v[20:23], v[222:225], v[198:201], v[20:23]
	v_mfma_f32_16x16x32_bf16 v[8:11], v[214:217], v[206:209], v[8:11]
	v_mfma_f32_16x16x32_bf16 v[4:7], v[222:225], v[206:209], v[4:7]
	v_mfma_f32_16x16x32_bf16 v[56:59], v[218:221], v[162:165], v[56:59]
	v_mfma_f32_16x16x32_bf16 v[52:55], v[226:229], v[162:165], v[52:55]
	v_mfma_f32_16x16x32_bf16 v[40:43], v[218:221], v[194:197], v[40:43]
	v_mfma_f32_16x16x32_bf16 v[36:39], v[226:229], v[194:197], v[36:39]
	v_mfma_f32_16x16x32_bf16 v[24:27], v[218:221], v[202:205], v[24:27]
	v_mfma_f32_16x16x32_bf16 v[20:23], v[226:229], v[202:205], v[20:23]
	v_mfma_f32_16x16x32_bf16 v[8:11], v[218:221], v[210:213], v[8:11]
	v_mfma_f32_16x16x32_bf16 v[4:7], v[226:229], v[210:213], v[4:7]
	s_setprio 0
	s_add_i32 s21, 0, 0x18000
	v_add_u32_e32 v80, s21, v168
	s_barrier
	ds_read_b128 v[68:71], v80
	ds_read_b128 v[72:75], v80 offset:1024
	ds_read_b128 v[76:79], v80 offset:2048
	ds_read_b128 v[80:83], v80 offset:3072
	s_add_u32 s30, s30, 0x200000
	s_addc_u32 s31, s31, 0
	s_mov_b32 m0, s42
	v_lshl_add_u64 v[214:215], s[30:31], 0, v[0:1]
	ds_read_b128 v[158:161], v189 offset:32768
	ds_read_b128 v[162:165], v189 offset:33792
	ds_read_b128 v[190:193], v189 offset:34816
	ds_read_b128 v[194:197], v189 offset:35840
	ds_read_b128 v[198:201], v189 offset:36864
	ds_read_b128 v[202:205], v189 offset:37888
	ds_read_b128 v[206:209], v189 offset:38912
	ds_read_b128 v[210:213], v189 offset:39936
	global_load_lds_dwordx4 v[214:215], off
	v_lshl_add_u64 v[214:215], s[30:31], 0, v[148:149]
	s_mov_b32 m0, s43
	s_nop 0
	global_load_lds_dwordx4 v[214:215], off
	s_waitcnt lgkmcnt(8)
	s_barrier
; #define G8_STAGE(bufoff, gbase, voff) do { _Pragma("unroll") for (int _i = 0; _i < 2; ++_i) \
;     __builtin_amdgcn_global_load_lds((const unsigned*)((const char*)(gbase) + (voff)[_i]), (LAS unsigned*)(lds + (bufoff) + ldsw + _i * 8192), 16, 0, 0); } while (0)
; #define G8_MMA(ai, bj, At, Bt) do { __builtin_amdgcn_s_setprio(1); _Pragma("unroll") for (int m = 0; m < 4; ++m) _Pragma("unroll") for (int n = 0; n < 2; ++n) _Pragma("unroll") for (int k = 0; k < 2; ++k) \
;     acc[ai][bj][m][n] = __builtin_amdgcn_mfma_f32_16x16x32_bf16(Bt[n][k], At[m][k], acc[ai][bj][m][n], 0, 0, 0); __builtin_amdgcn_s_setprio(0); } while (0)
; #define G8_WAIT_V(n) asm volatile("s_waitcnt vmcnt(" #n ")" ::: "memory")
; #define G8_WAIT_L(n) asm volatile("s_waitcnt lgkmcnt(" #n ")" ::: "memory")
; #define G8_BAR __builtin_amdgcn_s_barrier()
; #define G8_SCHED __builtin_amdgcn_sched_barrier(0)
; template <class Epi, class Sched>
; __device__ __forceinline__ void gemm_phase(const int wv_, LAS unsigned char* lds, const int lda, const int ldb, const int K, const Sched& S, const Epi& E) {
;     ...
;       G8_BAR; G8_WAIT_L(0); G8_MMA(1, 0, At, B0); G8_BAR; G8_SCHED;
;       G8_STAGE(G8_SB(1, 1), b3 + hstepB, voffB);
;       G8_WAIT_V(6); G8_BAR; G8_MMA(1, 1, At, B1); G8_BAR;
;     }
;     const bool zero = E(acc, cur, wr, wc, fr, fq);
	s_waitcnt lgkmcnt(0)
	s_setprio 1
	s_waitcnt lgkmcnt(0)
	v_mfma_f32_16x16x32_bf16 v[144:147], v[68:71], v[158:161], v[144:147]
	v_mfma_f32_16x16x32_bf16 v[140:143], v[76:79], v[158:161], v[140:143]
	v_mfma_f32_16x16x32_bf16 v[128:131], v[68:71], v[190:193], v[128:131]
	v_mfma_f32_16x16x32_bf16 v[124:127], v[76:79], v[190:193], v[124:127]
	v_mfma_f32_16x16x32_bf16 v[112:115], v[68:71], v[198:201], v[112:115]
	v_mfma_f32_16x16x32_bf16 v[108:111], v[76:79], v[198:201], v[108:111]
	v_mfma_f32_16x16x32_bf16 v[96:99], v[68:71], v[206:209], v[96:99]
	v_mfma_f32_16x16x32_bf16 v[92:95], v[76:79], v[206:209], v[92:95]
	v_mfma_f32_16x16x32_bf16 v[144:147], v[72:75], v[162:165], v[144:147]
	v_mfma_f32_16x16x32_bf16 v[140:143], v[80:83], v[162:165], v[140:143]
	v_mfma_f32_16x16x32_bf16 v[128:131], v[72:75], v[194:197], v[128:131]
	v_mfma_f32_16x16x32_bf16 v[124:127], v[80:83], v[194:197], v[124:127]
	v_mfma_f32_16x16x32_bf16 v[112:115], v[72:75], v[202:205], v[112:115]
	v_mfma_f32_16x16x32_bf16 v[108:111], v[80:83], v[202:205], v[108:111]
	v_mfma_f32_16x16x32_bf16 v[96:99], v[72:75], v[210:213], v[96:99]
	v_mfma_f32_16x16x32_bf16 v[92:95], v[80:83], v[210:213], v[92:95]
	s_setprio 0
	s_barrier
	s_add_i32 s30, 0, 0x1c000
	s_add_i32 s21, s21, s39
	v_add_u32_e32 v226, s30, v168
	v_lshl_add_u64 v[166:167], v[166:167], 0, s[90:91]
	s_mov_b32 m0, s21
	ds_read_b128 v[214:217], v226
	ds_read_b128 v[218:221], v226 offset:1024
	ds_read_b128 v[222:225], v226 offset:2048
	ds_read_b128 v[226:229], v226 offset:3072
	global_load_lds_dwordx4 v[166:167], off
	v_lshl_add_u64 v[166:167], v[230:231], 0, s[90:91]
	s_add_i32 m0, s21, 0x2000
	s_nop 0
	global_load_lds_dwordx4 v[166:167], off
	s_barrier
	s_waitcnt lgkmcnt(0)
	s_setprio 1
	s_waitcnt lgkmcnt(0)
	v_mfma_f32_16x16x32_bf16 v[136:139], v[214:217], v[158:161], v[136:139]
	v_mfma_f32_16x16x32_bf16 v[132:135], v[222:225], v[158:161], v[132:135]
	v_mfma_f32_16x16x32_bf16 v[120:123], v[214:217], v[190:193], v[120:123]
	v_mfma_f32_16x16x32_bf16 v[116:119], v[222:225], v[190:193], v[116:119]
	v_mfma_f32_16x16x32_bf16 v[104:107], v[214:217], v[198:201], v[104:107]
	v_mfma_f32_16x16x32_bf16 v[100:103], v[222:225], v[198:201], v[100:103]
	v_mfma_f32_16x16x32_bf16 v[88:91], v[214:217], v[206:209], v[88:91]
	v_mfma_f32_16x16x32_bf16 v[84:87], v[222:225], v[206:209], v[84:87]
	v_mfma_f32_16x16x32_bf16 v[136:139], v[218:221], v[162:165], v[136:139]
	v_mfma_f32_16x16x32_bf16 v[132:135], v[226:229], v[162:165], v[132:135]
	v_mfma_f32_16x16x32_bf16 v[120:123], v[218:221], v[194:197], v[120:123]
	v_mfma_f32_16x16x32_bf16 v[116:119], v[226:229], v[194:197], v[116:119]
	v_mfma_f32_16x16x32_bf16 v[104:107], v[218:221], v[202:205], v[104:107]
	v_mfma_f32_16x16x32_bf16 v[100:103], v[226:229], v[202:205], v[100:103]
	v_mfma_f32_16x16x32_bf16 v[88:91], v[218:221], v[210:213], v[88:91]
	v_mfma_f32_16x16x32_bf16 v[84:87], v[226:229], v[210:213], v[84:87]
	s_setprio 0
	s_mov_b32 m0, s46
	v_lshl_add_u64 v[166:167], v[232:233], 0, s[90:91]
	s_barrier
	ds_read_b128 v[158:161], v189 offset:49152
	ds_read_b128 v[162:165], v189 offset:50176
	ds_read_b128 v[190:193], v189 offset:51200
	ds_read_b128 v[194:197], v189 offset:52224
	ds_read_b128 v[198:201], v189 offset:53248
	ds_read_b128 v[202:205], v189 offset:54272
	ds_read_b128 v[206:209], v189 offset:55296
	ds_read_b128 v[210:213], v189 offset:56320
	global_load_lds_dwordx4 v[166:167], off
	v_lshl_add_u64 v[166:167], v[234:235], 0, s[90:91]
	s_mov_b32 m0, s47
	s_nop 0
	global_load_lds_dwordx4 v[166:167], off
	s_barrier
	s_waitcnt lgkmcnt(0)
	s_setprio 1
	s_waitcnt lgkmcnt(0)
	v_mfma_f32_16x16x32_bf16 v[64:67], v[68:71], v[158:161], v[64:67]
	v_mfma_f32_16x16x32_bf16 v[60:63], v[76:79], v[158:161], v[60:63]
	v_mfma_f32_16x16x32_bf16 v[48:51], v[68:71], v[190:193], v[48:51]
	v_mfma_f32_16x16x32_bf16 v[44:47], v[76:79], v[190:193], v[44:47]
	v_mfma_f32_16x16x32_bf16 v[32:35], v[68:71], v[198:201], v[32:35]
	v_mfma_f32_16x16x32_bf16 v[28:31], v[76:79], v[198:201], v[28:31]
	v_mfma_f32_16x16x32_bf16 v[16:19], v[68:71], v[206:209], v[16:19]
	v_mfma_f32_16x16x32_bf16 v[12:15], v[76:79], v[206:209], v[12:15]
	v_mfma_f32_16x16x32_bf16 v[64:67], v[72:75], v[162:165], v[64:67]
	v_mfma_f32_16x16x32_bf16 v[60:63], v[80:83], v[162:165], v[60:63]
	v_mfma_f32_16x16x32_bf16 v[48:51], v[72:75], v[194:197], v[48:51]
	v_mfma_f32_16x16x32_bf16 v[44:47], v[80:83], v[194:197], v[44:47]
	v_mfma_f32_16x16x32_bf16 v[32:35], v[72:75], v[202:205], v[32:35]
	v_mfma_f32_16x16x32_bf16 v[28:31], v[80:83], v[202:205], v[28:31]
	v_mfma_f32_16x16x32_bf16 v[16:19], v[72:75], v[210:213], v[16:19]
	v_mfma_f32_16x16x32_bf16 v[12:15], v[80:83], v[210:213], v[12:15]
	s_setprio 0
	s_barrier
	s_add_u32 s28, s28, 0x200080
	s_addc_u32 s29, s29, 0
	s_add_i32 s21, s30, s39
	v_lshl_add_u64 v[68:69], s[28:29], 0, v[0:1]
	s_mov_b32 m0, s21
	s_nop 0
	global_load_lds_dwordx4 v[68:69], off
	v_lshl_add_u64 v[68:69], s[28:29], 0, v[148:149]
	s_add_i32 m0, s21, 0x2000
	s_nop 0
	global_load_lds_dwordx4 v[68:69], off
	s_waitcnt vmcnt(6)
	s_barrier
	s_setprio 1
	v_mfma_f32_16x16x32_bf16 v[56:59], v[214:217], v[158:161], v[56:59]
	v_mfma_f32_16x16x32_bf16 v[52:55], v[222:225], v[158:161], v[52:55]
	v_mfma_f32_16x16x32_bf16 v[40:43], v[214:217], v[190:193], v[40:43]
	v_mfma_f32_16x16x32_bf16 v[36:39], v[222:225], v[190:193], v[36:39]
	v_mfma_f32_16x16x32_bf16 v[24:27], v[214:217], v[198:201], v[24:27]
	v_mfma_f32_16x16x32_bf16 v[20:23], v[222:225], v[198:201], v[20:23]
	v_mfma_f32_16x16x32_bf16 v[8:11], v[214:217], v[206:209], v[8:11]
	v_mfma_f32_16x16x32_bf16 v[4:7], v[222:225], v[206:209], v[4:7]
	v_mfma_f32_16x16x32_bf16 v[56:59], v[218:221], v[162:165], v[56:59]
	v_mfma_f32_16x16x32_bf16 v[52:55], v[226:229], v[162:165], v[52:55]
	v_mfma_f32_16x16x32_bf16 v[40:43], v[218:221], v[194:197], v[40:43]
	v_mfma_f32_16x16x32_bf16 v[36:39], v[226:229], v[194:197], v[36:39]
	v_mfma_f32_16x16x32_bf16 v[24:27], v[218:221], v[202:205], v[24:27]
	v_mfma_f32_16x16x32_bf16 v[20:23], v[226:229], v[202:205], v[20:23]
	v_mfma_f32_16x16x32_bf16 v[8:11], v[218:221], v[210:213], v[8:11]
	v_mfma_f32_16x16x32_bf16 v[4:7], v[226:229], v[210:213], v[4:7]
	s_setprio 0
	s_add_i32 s19, s19, 2
	s_add_u32 s26, s26, 0x100
	s_addc_u32 s27, s27, 0
	s_add_u32 s9, s9, 0x100
	s_addc_u32 s11, s11, 0
	s_cmpk_gt_u32 s19, 0x7d
	s_barrier
	s_cbranch_scc0 .LBB0_1246
	v_readlane_b32 s9, v242, 62
	s_cmp_eq_u32 s50, 3
	s_cselect_b32 s9, s9, 0
	s_cmp_lg_u32 s9, 0
	s_cbranch_scc1 .Lg5s_epi
	v_lshl_or_b32 v158, s18, 8, v169
	s_mul_hi_i32 s11, s20, 0x78787879
	s_lshr_b32 s9, s11, 31
	s_ashr_i32 s11, s11, 3
	s_add_i32 s11, s11, s9
	s_lshl_b32 s9, s20, 8
	s_mul_i32 s18, s11, 0xffffef00
	s_add_i32 s18, s18, s9
	s_cmpk_gt_i32 s18, 0xff
	s_cbranch_scc1 .Lg5e_lat
	s_load_dwordx2 s[20:21], s[0:1], 0x118
	s_lshl_b32 s9, s11, 21
	s_mov_b32 s11, 4
	s_waitcnt lgkmcnt(0)
	s_add_u32 s20, s20, 0x7f8000
	s_addc_u32 s21, s21, 0
	s_branch .Lg5e_ptr

; #define p (kparams())
;   __device__ __forceinline__ bool operator()(f32x4 (&acc)[2][2][4][2], const Unit& u, int wr, int wc, int fr, int fq) const {
;     const int row0 = u.pm * BM + wr * 64 + fr, col0 = u.pn * BM + wc * 32 + 4 * fq;
;     const int who = row_who(u.pm * BM);
;     const float* gp = modl + (size_t)who * 12288 + part * 2048 + col0;
;     f32x4 gv[2][2];
; #pragma unroll
;     for (int bj = 0; bj < 2; ++bj)
; #pragma unroll
;       for (int n = 0; n < 2; ++n) gv[bj][n] = *(const f32x4*)(gp + bj * HALF + n * 16);
; #pragma unroll
;     for (int ai = 0; ai < 2; ++ai)
; #pragma unroll
;       for (int m = 0; m < 4; ++m) { const int row = row0 + ai * HALF + m * 16;
;         KPR p = (KParams*)__builtin_amdgcn_kernarg_segment_ptr();
;         const float* src = xrow_ptr(p, layer_src, row) + col0; float* dst = xrow_dst(p, row) + col0;
; #pragma unroll
;         for (int bj = 0; bj < 2; ++bj)
; #pragma unroll
;           for (int n = 0; n < 2; ++n) {
;             if (u.split) { const f32x4 dv = gv[bj][n] * acc[ai][bj][m][n]; float* dp = dst + bj * HALF + n * 16;
;               unsafeAtomicAdd(dp, dv[0]); unsafeAtomicAdd(dp + 1, dv[1]); unsafeAtomicAdd(dp + 2, dv[2]); unsafeAtomicAdd(dp + 3, dv[3]); }
;             else { const f32x4 xi = *(const f32x4*)(src + bj * HALF + n * 16);
;               *(f32x4*)(dst + bj * HALF + n * 16) = xi + gv[bj][n] * acc[ai][bj][m][n]; } } }
.Lg5s_epi:
	s_lshr_b32 s9, s20, 4
	s_lshl_b32 s9, s9, 21
	s_lshl_b32 s11, s18, 10
	s_add_i32 s9, s9, s11
	s_and_b32 s11, s2, 7
	s_lshl_b32 s11, s11, 23
	s_add_i32 s9, s9, s11
	s_load_dwordx2 s[20:21], s[0:1], 0x118
	v_lshlrev_b32_e32 v160, 2, v169
	v_lshl_add_u32 v160, v3, 13, v160
	v_mov_b32_e32 v161, 0
	s_waitcnt lgkmcnt(0)
	s_add_u32 s20, s20, 0xa4e0000
	s_addc_u32 s21, s21, 0
	s_add_u32 s20, s20, s9
	s_addc_u32 s21, s21, 0
	v_lshl_add_u64 v[166:167], v[160:161], 0, s[20:21]
	s_mov_b32 s18, 0x20000
	s_mov_b32 s19, 0
	global_store_dwordx4 v[166:167], v[144:147], off
	global_store_dwordx4 v[166:167], v[140:143], off offset:64
	global_store_dwordx4 v[166:167], v[136:139], off offset:512
	global_store_dwordx4 v[166:167], v[132:135], off offset:576
	v_lshl_add_u64 v[166:167], v[166:167], 0, s[18:19]
	global_store_dwordx4 v[166:167], v[128:131], off
	global_store_dwordx4 v[166:167], v[124:127], off offset:64
	global_store_dwordx4 v[166:167], v[120:123], off offset:512
	global_store_dwordx4 v[166:167], v[116:119], off offset:576
	v_lshl_add_u64 v[166:167], v[166:167], 0, s[18:19]
	global_store_dwordx4 v[166:167], v[112:115], off
	global_store_dwordx4 v[166:167], v[108:111], off offset:64
	global_store_dwordx4 v[166:167], v[104:107], off offset:512
	global_store_dwordx4 v[166:167], v[100:103], off offset:576
	v_lshl_add_u64 v[166:167], v[166:167], 0, s[18:19]
	global_store_dwordx4 v[166:167], v[96:99], off
	global_store_dwordx4 v[166:167], v[92:95], off offset:64
	global_store_dwordx4 v[166:167], v[88:91], off offset:512
	global_store_dwordx4 v[166:167], v[84:87], off offset:576
	s_mov_b32 s18, 0xa0000
	v_lshl_add_u64 v[166:167], v[166:167], 0, s[18:19]
	s_mov_b32 s18, 0x20000
	global_store_dwordx4 v[166:167], v[64:67], off
	global_store_dwordx4 v[166:167], v[60:63], off offset:64
	global_store_dwordx4 v[166:167], v[56:59], off offset:512
	global_store_dwordx4 v[166:167], v[52:55], off offset:576
	v_lshl_add_u64 v[166:167], v[166:167], 0, s[18:19]
	global_store_dwordx4 v[166:167], v[48:51], off
	global_store_dwordx4 v[166:167], v[44:47], off offset:64
	global_store_dwordx4 v[166:167], v[40:43], off offset:512
	global_store_dwordx4 v[166:167], v[36:39], off offset:576
	v_lshl_add_u64 v[166:167], v[166:167], 0, s[18:19]
	global_store_dwordx4 v[166:167], v[32:35], off
	global_store_dwordx4 v[166:167], v[28:31], off offset:64
	global_store_dwordx4 v[166:167], v[24:27], off offset:512
	global_store_dwordx4 v[166:167], v[20:23], off offset:576
	v_lshl_add_u64 v[166:167], v[166:167], 0, s[18:19]
	global_store_dwordx4 v[166:167], v[16:19], off
	global_store_dwordx4 v[166:167], v[12:15], off offset:64
	global_store_dwordx4 v[166:167], v[8:11], off offset:512
	global_store_dwordx4 v[166:167], v[4:7], off offset:576
	s_branch .LBB0_1240
